# P2 unit ids relabelled so each XCD handles the two batches whose rows it produces in P1 and consumes in P3; P1->P2 and P2->P3 grid barriers become XCD-local (no flush, no cross-XCD stage) when the pla
# speedup vs baseline: 1.0117x; 1.0057x over previous
; #define PG8_WAIT_V(n) asm volatile("s_waitcnt vmcnt(" #n ")" ::: "memory")
; #define PG8_BAR __builtin_amdgcn_s_barrier()
; template <class Epi, class Sched>
; __device__ __forceinline__ void gemm_phase(LAS unsigned char* lds, const Gemm g, const Sched& S, const Epi& E) {
;     int tid_ = threadIdx.x; asm volatile("" : "+v"(tid_));
;     const int tid = tid_, wid = __builtin_amdgcn_readfirstlane(tid >> 6), lane = tid & 63, wr = wid >> 2, wc = wid & 3, fr = lane & 15, fq = lane >> 4;
;     const int K = g.K, nt = K / BK;
;     unsigned voffA[2], voffB[2];
; #pragma unroll
;     for (int i = 0; i < 2; ++i) { int R, C; stage_rc(tid * 16 + i * 8192, R, C);
;         const int Ra = 128 * (R >> 6) + (R & 63);
;         const int Rb = Epi::HEADPERM ? (64 * (R >> 5) + perm32(R & 31)) : ((R & ~31) + perm32(R & 31));
;         voffA[i] = (unsigned)(Ra * g.lda + C) * 2u; voffB[i] = (unsigned)(Rb * K + C) * 2u; }
;     const size_t kstep = (size_t)(BK * 2);
;     const size_t hstepA = (size_t)64 * g.lda * 2, kstepA = (size_t)g.kstepA;
;     const size_t hstepB = (size_t)(Epi::HEADPERM ? 32 : 128) * K * 2;
;     const size_t tstep = (size_t)256 * K * 2;
;     const unsigned ldsw = (unsigned)wid * 1024u;
;     const unsigned lds_u32 = (unsigned)(size_t)lds;
;     const int aoff = lds_byte(wr * 64 + fr, fq * 8), boff = lds_byte(wc * 32 + fr, fq * 8);
;     ...
;     const char* cA = (const char*)g.A + (size_t)cur.pm * tstep; const char* cB = (const char*)g.Bt + (size_t)cur.pn * tstep;
;     PG8_STAGE(PG8_SB(0, 0), cB, voffB); PG8_STAGE(PG8_SB(0, 1), cB + hstepB, voffB); PG8_STAGE(PG8_SA(0, 0), cA, voffA); PG8_STAGE(PG8_SA(0, 1), cA + hstepA, voffA);
;     if (wr == 1) PG8_BAR;
;     PG8_WAIT_V(2); PG8_BAR;
;     PG8_STAGE(PG8_SB(1, 0), cB + kstep, voffB); PG8_STAGE(PG8_SA(1, 0), cA + kstepA, voffA); PG8_STAGE(PG8_SB(1, 1), cB + hstepB + kstep, voffB);
.LBB0_86:
	s_or_b64 exec, exec, s[0:1]
	s_add_u32 s42, s84, 0x2000000
	s_addc_u32 s43, s85, 0
	s_add_u32 s46, s84, 0x6000000
	s_addc_u32 s47, s85, 0
	s_add_u32 s50, s84, 0x8000000
	s_addc_u32 s51, s85, 0
	s_add_u32 s52, s84, 0xa000000
	s_addc_u32 s53, s85, 0
	s_waitcnt lgkmcnt(0)
	v_mov_b32_e32 v2, v0
	s_ashr_i32 s33, s2, 31
	s_barrier
	v_mov_b32_e32 v240, 0x3800
	global_load_dword v241, v240, s[84:85] sc1
	s_waitcnt vmcnt(0)
	v_readfirstlane_b32 s32, v241
	s_cmpk_gt_i32 s2, 0x4ff
	v_readfirstlane_b32 s5, v2
	s_cbranch_scc1 .LBB0_112
	v_bfe_i32 v5, v2, 27, 1
	v_lshlrev_b32_e32 v3, 4, v2
	v_lshrrev_b32_e32 v5, 22, v5
	v_add_u32_e32 v5, v3, v5
	v_and_b32_e32 v5, 0xfffffc00, v5
	v_sub_u32_e32 v5, v3, v5
	v_ashrrev_i32_e32 v4, 31, v2
	v_lshrrev_b32_e32 v6, 4, v5
	v_lshrrev_b32_e32 v4, 26, v4
	v_bitop3_b32 v5, v6, v5, 32 bitop3:0x6c
	v_add_u32_e32 v4, v2, v4
	v_ashrrev_i32_e32 v7, 31, v5
	v_ashrrev_i32_e32 v4, 6, v4
	v_lshrrev_b32_e32 v7, 26, v7
	v_lshlrev_b32_e32 v6, 3, v4
	v_add_u32_e32 v7, v5, v7
	v_and_b32_e32 v6, -16, v6
	v_ashrrev_i32_e32 v8, 6, v7
	v_and_b32_e32 v7, 0xc0, v7
	v_add_u32_e32 v6, v8, v6
	v_sub_u32_e32 v5, v5, v7
	v_mov_b32_e32 v7, 1
	v_lshlrev_b32_e32 v4, 5, v4
	v_ashrrev_i16_sdwa v5, v7, sext(v5) dst_sel:DWORD dst_unused:UNUSED_PAD src0_sel:DWORD src1_sel:BYTE_0
	v_lshlrev_b32_e32 v9, 1, v6
	v_and_b32_e32 v10, 63, v6
	s_mov_b32 s0, 0x1fff80
	v_lshrrev_b32_e32 v6, 2, v6
	v_and_b32_e32 v4, 32, v4
	v_bfe_i32 v5, v5, 0, 16
	v_and_or_b32 v10, v9, s0, v10
	v_and_b32_e32 v6, 4, v6
	v_and_b32_e32 v8, 3, v8
	v_and_b32_e32 v9, 0x1fffd8, v9
	v_or3_b32 v6, v8, v6, v9
	v_add_lshl_u32 v4, v4, v5, 1
	v_add_u32_e32 v3, 0x2000, v3
	v_lshl_add_u32 v131, v10, 11, v4
	v_lshl_add_u32 v144, v6, 11, v4
	v_ashrrev_i32_e32 v4, 31, v3
	v_lshrrev_b32_e32 v4, 22, v4
	v_add_u32_e32 v4, v3, v4
	v_ashrrev_i32_e32 v4, 10, v4
	v_mul_i32_i24_e32 v5, 0x400, v4
	v_sub_u32_e32 v3, v3, v5
	v_lshrrev_b32_e32 v5, 4, v3
	v_bitop3_b32 v3, v5, v3, 32 bitop3:0x6c
	v_ashrrev_i32_e32 v6, 31, v3
	v_lshrrev_b32_e32 v6, 26, v6
	v_lshlrev_b32_e32 v5, 3, v4
	v_add_u32_e32 v6, v3, v6
	v_and_b32_e32 v5, -16, v5
	v_ashrrev_i32_e32 v8, 6, v6
	v_and_b32_e32 v6, 0xc0, v6
	v_add_u32_e32 v5, v8, v5
	v_sub_u32_e32 v3, v3, v6
	v_ashrrev_i16_sdwa v3, v7, sext(v3) dst_sel:DWORD dst_unused:UNUSED_PAD src0_sel:DWORD src1_sel:BYTE_0
	v_lshlrev_b32_e32 v6, 1, v5
	v_and_b32_e32 v7, 63, v5
	v_and_or_b32 v7, v6, s0, v7
	s_mul_hi_i32 s0, s2, 0x66666667
	s_lshr_b32 s1, s0, 31
	s_lshr_b32 s0, s0, 9
	s_add_i32 s0, s0, s1
	s_mulk_i32 s0, 0x500
	s_sub_i32 s0, s2, s0
	s_sext_i32_i16 s1, s0
	s_bfe_u32 s1, s1, 0x3001c
	s_add_i32 s1, s0, s1
	s_sext_i32_i16 s4, s1
	s_and_b32 s1, s1, 0xfff8
	s_ashr_i32 s8, s5, 6
	s_sub_i32 s0, s0, s1
	s_ashr_i32 s11, s5, 8
	s_lshl_b32 s10, s8, 10
	s_ashr_i32 s4, s4, 3
	s_sext_i32_i16 s1, s0
	s_cmp_lt_i32 s1, 0
	s_movk_i32 s21, 0xa1
	s_cselect_b32 s1, s21, 0xa0
	s_mul_i32 s0, s0, s1
	s_add_i32 s0, s0, s4
	s_sext_i32_i16 s1, s0
	s_mulk_i32 s1, 0x6667
	s_lshr_b32 s4, s1, 31
	s_ashr_i32 s1, s1, 21
	s_add_i32 s1, s1, s4
	s_lshl_b32 s9, s1, 3
	s_mulk_i32 s1, 0x50
	s_sub_i32 s0, s0, s1
	s_bfe_i32 s1, s0, 0x80000
	s_bfe_u32 s1, s1, 0x3000c
	s_add_i32 s1, s0, s1
	s_bfe_i32 s4, s1, 0x80000
	s_and_b32 s1, s1, 0xf8
	s_sub_i32 s0, s0, s1
	s_sext_i32_i16 s4, s4
	s_sext_i32_i8 s0, s0
	s_lshr_b32 s4, s4, 3
	s_add_i32 s18, s9, s0
	s_ashr_i32 s19, s18, 31
	s_bfe_i64 s[12:13], s[4:5], 0x100000
	s_lshl_b64 s[0:1], s[18:19], 19
	s_lshl_b64 s[12:13], s[12:13], 19
	v_lshlrev_b32_e32 v4, 5, v4
	v_lshrrev_b32_e32 v5, 2, v5
	s_add_u32 s26, s6, s12
	v_and_b32_e32 v4, 32, v4
	v_bfe_i32 v3, v3, 0, 16
	v_and_b32_e32 v5, 4, v5
	v_and_b32_e32 v8, 3, v8
	v_and_b32_e32 v6, 0x1fffd8, v6
	s_addc_u32 s27, s7, s13
	s_add_i32 s12, s10, 0
	v_or3_b32 v5, v8, v5, v6
	v_add_lshl_u32 v3, v4, v3, 1
	s_add_i32 s13, s12, 0x10000
	s_mov_b32 m0, s13
	s_nop 0
	global_load_lds_dwordx4 v144, s[26:27]
	s_add_i32 s14, s12, 0x12000
	s_add_i32 s15, s12, 0x14000
	v_lshl_add_u32 v146, v5, 11, v3
	s_mov_b32 m0, s14
	s_nop 0
	global_load_lds_dwordx4 v146, s[26:27]
	s_add_u32 s24, s26, 0x10000
	s_addc_u32 s25, s27, 0
	s_mov_b32 m0, s15
	s_nop 0
	global_load_lds_dwordx4 v144, s[24:25]
	s_add_i32 s16, s12, 0x16000
	s_mov_b32 m0, s16
	s_nop 0
	global_load_lds_dwordx4 v146, s[24:25]
	s_add_u32 s24, s42, s0
	s_addc_u32 s25, s43, s1
	s_mov_b32 m0, s12
	s_nop 0
	global_load_lds_dwordx4 v131, s[24:25]
	s_add_i32 s17, s12, 0x2000
	s_add_i32 s19, s12, 0x4000
	v_lshl_add_u32 v145, v7, 11, v3
	s_mov_b32 m0, s17
	s_nop 0
	global_load_lds_dwordx4 v145, s[24:25]
	s_add_u32 s30, s24, 0x20000
	s_addc_u32 s31, s25, 0
	s_mov_b32 m0, s19
	s_nop 0
	global_load_lds_dwordx4 v131, s[30:31]
	s_add_i32 s28, s12, 0x6000
	s_mov_b32 m0, s28
	s_nop 0
	global_load_lds_dwordx4 v145, s[30:31]
	s_cmp_eq_u32 s11, 1
	s_mov_b32 s20, 0
	s_mov_b32 s22, 0x10000
	s_mov_b32 s23, 0x14000
	s_movk_i32 s36, 0x4000
	s_cselect_b64 s[0:1], -1, 0
	s_cmp_lg_u32 s11, 1
	s_cbranch_scc1 .LBB0_89
	s_barrier

; __device__ __forceinline__ unsigned xb_ld(unsigned* p)              { return __hip_atomic_load(p, __ATOMIC_RELAXED, __HIP_MEMORY_SCOPE_AGENT); }
; #define XB_SPIN(cond, bar) do { unsigned _sp = 0; while (cond) { __builtin_amdgcn_s_sleep(1); \
;     if ((++_sp & 255u) == 0u) { if (xb_ld(&(bar)[XB_TMO])) break; if (_sp > XB_SPIN_CAP) { atomicAdd(&(bar)[XB_TMO], 1u); break; } } } } while (0)
; __device__ __forceinline__ void xcd_barrier(const XcdBarrier& b) {
;     ...
;             XB_SPIN(xb_ld(&bar[XB_XGEN(b.x)]) == gen, bar);
;             __builtin_amdgcn_fence(__ATOMIC_ACQUIRE, "agent");
;             asm volatile("s_waitcnt vmcnt(0)" ::: "memory");
.LBB0_143:
	s_or_b64 exec, exec, s[8:9]
	s_waitcnt vmcnt(0)
	s_cmp_eq_u32 s32, 0
	s_cbranch_scc1 .Lxb1_a
	buffer_inv sc1

; __device__ __forceinline__ unsigned xb_add(unsigned* p, unsigned v) { return __hip_atomic_fetch_add(p, v, __ATOMIC_RELAXED, __HIP_MEMORY_SCOPE_AGENT); }
; __device__ __forceinline__ void xcd_barrier(const XcdBarrier& b) {
;     ...
;         if (old + 1u == (gen + 1u) * nloc) {
;             __builtin_amdgcn_fence(__ATOMIC_RELEASE, "agent");
;             asm volatile("s_waitcnt vmcnt(0)" ::: "memory");
;             const unsigned og = xb_add(&bar[XB_TOP], 1u);
;             const unsigned tg = og / nx;
;             if (og + 1u == (tg + 1u) * nx) xb_add(&bar[XB_TOPGEN], 1u);
.LBB0_144:
	s_andn2_saveexec_b64 s[6:7], s[6:7]
	s_cbranch_execz .LBB0_164
	s_mov_b64 s[6:7], exec
	s_cmp_eq_u32 s32, 0
	s_cbranch_scc1 .Lxb1_rel
	buffer_wbl2 sc1
	s_waitcnt lgkmcnt(0)
	s_waitcnt vmcnt(0)
	v_mbcnt_lo_u32_b32 v3, s6, 0
	v_mbcnt_hi_u32_b32 v3, s7, v3
	v_cmp_eq_u32_e32 vcc, 0, v3
	s_and_saveexec_b64 s[8:9], vcc
	s_cbranch_execz .LBB0_147
	s_bcnt1_i32_b64 s6, s[6:7]
	v_mov_b32_e32 v4, 0x3000
	v_mov_b32_e32 v5, s6
	global_atomic_add v4, v4, v5, s[84:85] offset:1024 sc0

; __device__ __forceinline__ unsigned xb_add(unsigned* p, unsigned v) { return __hip_atomic_fetch_add(p, v, __ATOMIC_RELAXED, __HIP_MEMORY_SCOPE_AGENT); }
; __device__ __forceinline__ void xcd_barrier(const XcdBarrier& b) {
;     ...
;             __builtin_amdgcn_fence(__ATOMIC_ACQUIRE, "agent");
;             xb_add(&bar[XB_XGEN(b.x)], 1u);
;             asm volatile("s_waitcnt vmcnt(0)" ::: "memory");
.Lxb1_rel:
.LBB0_161:
	s_or_b64 exec, exec, s[6:7]
	s_mov_b64 s[6:7], exec
	v_mbcnt_lo_u32_b32 v2, s6, 0
	v_mbcnt_hi_u32_b32 v2, s7, v2
	v_cmp_eq_u32_e32 vcc, 0, v2
	s_waitcnt vmcnt(0)
	s_cmp_eq_u32 s32, 0
	s_cbranch_scc1 .Lxb1_b
	buffer_inv sc1
.Lxb1_b:
	s_and_saveexec_b64 s[8:9], vcc
	s_cbranch_execz .LBB0_163
	s_bcnt1_i32_b64 s6, s[6:7]
	v_mov_b32_e32 v2, 0x2000
	v_mov_b32_e32 v3, s6
	global_atomic_add v2, v3, s[4:5] offset:1024

; #define LAS __attribute__((address_space(3)))
; __global__ void __launch_bounds__(512, 2) mk_fwd(Args args) {
;     ...
;         const AttnP AP{Qb, Kb, Vt, MIX, ssqA, q_norm_g, k_norm_g};
;         if (wave == 0) { unsigned long long T[18]; attn_tables(lane, T); LAS unsigned long long* D = (LAS unsigned long long*)(lds + LDS_ATAB + lane * 144);
; #pragma unroll
;             for (int k = 0; k < 18; ++k) D[k] = T[k]; }
;         __syncthreads();
;         for (int p = bx; p < 256 * REP_P2; p += G) { const int pp = p & 255, hd = pp & 7, qa = (pp >> 3) & 1, b = pp >> 4;
;             attn_unit(AP, lds, b, hd, 3 - qa, wave, lane); attn_unit(AP, lds, b, hd, qa, wave, lane); }
.LBB0_166:
	s_add_u32 s34, s84, 0x1a00000
	s_addc_u32 s35, s85, 0
	s_add_u32 s0, s84, 0x10000000
	s_addc_u32 s1, s85, 0
	v_writelane_b32 v243, s0, 20
	s_cmpk_lt_i32 s2, 0x100
	s_waitcnt lgkmcnt(0)
	v_writelane_b32 v243, s1, 21
	s_cselect_b64 s[0:1], -1, 0
	v_writelane_b32 v243, s0, 22
	s_cmpk_gt_i32 s2, 0xff
	s_barrier
	v_writelane_b32 v243, s1, 23
	s_cbranch_scc1 .LBB0_545
	v_writelane_b32 v243, s66, 24
	v_writelane_b32 v243, s94, 26
	v_mbcnt_lo_u32_b32 v1, -1, 0
	v_mbcnt_hi_u32_b32 v215, -1, v1
	v_writelane_b32 v243, s95, 27
	v_writelane_b32 v243, s86, 28
	v_lshlrev_b32_e32 v190, 2, v201
	v_mov_b32_e32 v191, 0
	v_writelane_b32 v243, s87, 29
	v_writelane_b32 v243, s67, 30
	v_mov_b32_e32 v82, 0x3f803f80
	v_readlane_b32 s4, v243, 4
	v_readlane_b32 s6, v243, 6
	v_readlane_b32 s7, v243, 7
	v_readlane_b32 s8, v243, 8
	v_readlane_b32 s9, v243, 9
	v_readlane_b32 s10, v243, 10
	v_readlane_b32 s11, v243, 11
	v_readlane_b32 s12, v243, 12
	v_readlane_b32 s13, v243, 13
	v_readlane_b32 s14, v243, 14
	v_readlane_b32 s15, v243, 15
	v_readlane_b32 s16, v243, 16
	v_readlane_b32 s17, v243, 17
	s_mov_b64 s[6:7], s[10:11]
	s_mov_b64 s[8:9], s[12:13]
	v_and_b32_e32 v1, 64, v215
	v_lshl_add_u64 v[192:193], s[6:7], 0, v[190:191]
	v_lshl_add_u64 v[194:195], s[8:9], 0, v[190:191]
	s_add_i32 s62, s92, 1
	s_add_i32 s63, s92, 4
	s_add_i32 s64, s92, 8
	s_add_i32 s65, s92, 9
	s_add_i32 s70, s92, 12
	s_mov_b32 s59, 0
	s_movk_i32 s71, 0xa0
	s_add_i32 s93, 0, 0x14000
	s_mov_b32 s30, 0x41f00000
	s_movk_i32 s31, 0x90
	v_mov_b32_e32 v83, v82
	v_mov_b32_e32 v84, v82
	v_mov_b32_e32 v85, v82
	v_mov_b32_e32 v214, 0xffff6000
	s_movk_i32 s36, 0xfec0
	v_add_u32_e32 v216, 64, v1
	v_xor_b32_e32 v217, 1, v215
	v_xor_b32_e32 v218, 2, v215
	v_xor_b32_e32 v219, 4, v215
	v_xor_b32_e32 v220, 8, v215
	v_xor_b32_e32 v221, 16, v215
	v_xor_b32_e32 v222, 32, v215
	v_mov_b32_e32 v196, 0x1010101
	s_mov_b32 s97, s2
	s_cmp_lg_u32 s3, 0x100
	s_cbranch_scc1 .Lattn_noremap
	s_and_b32 s97, s2, 7
	s_lshl_b32 s97, s97, 5
	s_lshr_b32 s101, s2, 3
	s_or_b32 s97, s97, s101
.Lattn_noremap:
	v_readlane_b32 s5, v243, 5
	v_readlane_b32 s18, v243, 18
	v_readlane_b32 s19, v243, 19
	s_mov_b64 s[10:11], s[14:15]
	s_mov_b64 s[12:13], s[16:17]
	s_branch .LBB0_169

; __device__ __forceinline__ void gmlp_unit(const GmlpP& P, int b, int ch, LAS unsigned char* lds, int wave, int lane_in) {
;     ...
;     const size_t tok0 = (size_t)b * SEQ + (size_t)ch * 128;
; __global__ void __launch_bounds__(512, 2) mk_fwd(Args args) {
;     ...
;         for (int a = bx; a < 256 * REP_GM; a += G) gmlp_unit(GP, (a & 255) >> 4, a & 15, lds, wave, lane);
.Lgmlp_paired:
	s_mov_b32 s100, 8
	s_movk_i32 s39, 0x400
	s_and_b32 s49, s2, 7
	s_lshl_b32 s49, s49, 5
	s_lshr_b32 s101, s2, 3
	s_or_b32 s49, s49, s101
	s_lshl_b32 s38, s49, 7
	s_add_i32 s101, s49, 8
	s_bitcmp1_b32 s49, 3
	s_cbranch_scc1 .LBB0_545
	s_branch .LBB0_537

; __device__ __forceinline__ unsigned xb_add(unsigned* p, unsigned v) { return __hip_atomic_fetch_add(p, v, __ATOMIC_RELAXED, __HIP_MEMORY_SCOPE_AGENT); }
; __device__ __forceinline__ void xcd_barrier(const XcdBarrier& b) {
;     ...
;         if (old + 1u == (gen + 1u) * nloc) {
;             __builtin_amdgcn_fence(__ATOMIC_RELEASE, "agent");
;             asm volatile("s_waitcnt vmcnt(0)" ::: "memory");
;             const unsigned og = xb_add(&bar[XB_TOP], 1u);
;             const unsigned tg = og / nx;
;             if (og + 1u == (tg + 1u) * nx) xb_add(&bar[XB_TOPGEN], 1u);
.LBB0_577:
	s_andn2_saveexec_b64 s[6:7], s[6:7]
	s_cbranch_execz .LBB0_597
	s_mov_b64 s[6:7], exec
	s_cmp_eq_u32 s32, 0
	s_cbranch_scc1 .Lxb2_rel
	buffer_wbl2 sc1
	s_waitcnt lgkmcnt(0)
	s_waitcnt vmcnt(0)
	v_mbcnt_lo_u32_b32 v2, s6, 0
	v_mbcnt_hi_u32_b32 v2, s7, v2
	v_cmp_eq_u32_e32 vcc, 0, v2
	s_and_saveexec_b64 s[8:9], vcc
	s_cbranch_execz .LBB0_580
	s_bcnt1_i32_b64 s6, s[6:7]
	v_mov_b32_e32 v3, 0x3000
	v_mov_b32_e32 v4, s6
	global_atomic_add v3, v3, v4, s[84:85] offset:1024 sc0

; __device__ __forceinline__ unsigned xb_add(unsigned* p, unsigned v) { return __hip_atomic_fetch_add(p, v, __ATOMIC_RELAXED, __HIP_MEMORY_SCOPE_AGENT); }
; __device__ __forceinline__ void xcd_barrier(const XcdBarrier& b) {
;     ...
;             __builtin_amdgcn_fence(__ATOMIC_ACQUIRE, "agent");
;             xb_add(&bar[XB_XGEN(b.x)], 1u);
;             asm volatile("s_waitcnt vmcnt(0)" ::: "memory");
.Lxb2_rel:
.LBB0_594:
	s_or_b64 exec, exec, s[6:7]
	s_mov_b64 s[6:7], exec
	v_mbcnt_lo_u32_b32 v1, s6, 0
	v_mbcnt_hi_u32_b32 v1, s7, v1
	v_cmp_eq_u32_e32 vcc, 0, v1
	s_waitcnt vmcnt(0)
	s_cmp_eq_u32 s32, 0
	s_cbranch_scc1 .Lxb2_b
	buffer_inv sc1
.Lxb2_b:
	s_and_saveexec_b64 s[8:9], vcc
	s_cbranch_execz .LBB0_596
	s_bcnt1_i32_b64 s6, s[6:7]
	v_mov_b32_e32 v1, 0x2000
	v_mov_b32_e32 v2, s6
	global_atomic_add v1, v2, s[4:5] offset:1024
